# v23 + SWA epilogue store widening, with a 32-byte pad after the DA code so the GEMM loops keep v23's 64-byte placement
# speedup vs baseline: 1.0065x; 1.0016x over previous
.LBB0_745:
	s_nop 0
	s_nop 0
	s_nop 0
	s_nop 0
	s_nop 0
	s_nop 0
	s_nop 0
	s_nop 0
	s_mov_b64 s[0:1], 0
